# weight conversion moved out of the attention loops: streaming routine in P0 (layer 0 + next W_in) and on the 128 workgroups idle in the last round of layer-0 gate/up GEMM (layer 1)
# speedup vs baseline: 1.0380x; 1.0131x over previous
.LBB0_32:
	s_add_u32 s24, s20, 0x7600000
	s_addc_u32 s25, s21, 0
	s_add_u32 s46, s20, 0x280000
	s_addc_u32 s47, s21, 0
	s_bfe_u32 s15, s12, 0x10007
	v_mov_b32_e32 v0, 0x6050400
	s_lshl_b32 s16, s15, 24
	v_perm_b32 v165, s12, v164, v0
	s_add_u32 s16, s24, s16
	v_and_b32_e32 v0, 0x7fff, v165
	s_addc_u32 s17, s25, 0
	s_lshl_b32 s15, s15, 12
	v_lshlrev_b32_e32 v162, 2, v0
	s_add_u32 s15, s46, s15
	v_lshl_add_u64 v[166:167], s[16:17], 0, v[162:163]
	s_addc_u32 s16, s47, 0
	s_lshr_b32 s17, s12, 2
	s_and_b32 s17, s17, 28
	s_mov_b32 s0, 0x10000
	v_cmp_gt_i32_e64 s[22:23], s2, v164
	s_add_u32 s58, s15, s17
	v_cmp_gt_i32_e32 vcc, s0, v165
	s_addc_u32 s59, s16, 0
	s_and_b64 s[16:17], s[22:23], vcc
	v_cndmask_b32_e64 v168, v219, 0, s[16:17]
	s_add_i32 s15, s68, 5
	s_lshl_b32 s81, s80, 2
	s_lshl_b32 s16, s12, 2
	s_cmp_lt_u32 s15, 13
	s_movk_i32 s15, 0x3d00
	s_cselect_b32 s15, s15, 0x6200
	s_movk_i32 s17, 0x3500
	s_cselect_b32 s17, s17, 0x5e00
	v_mov_b32_e32 v1, s15
	s_movk_i32 s15, 0xbfc
	v_mov_b32_e32 v0, s17
	s_cselect_b32 s15, s15, 0x3cfc
	v_cndmask_b32_e64 v230, v0, v1, s[22:23]
	v_mov_b32_e32 v1, s15
	v_writelane_b32 v255, s22, 8
	s_add_i32 s15, s37, s16
	v_lshrrev_b32_e32 v232, 2, v229
	v_cndmask_b32_e64 v0, v1, v0, s[22:23]
	v_add_u32_e32 v231, s15, v0
	v_mov_b32_e32 v231, v230
	s_mul_i32 s15, s37, 0x1100
	s_add_i32 s15, s15, 0
	v_writelane_b32 v255, s23, 9
	s_add_i32 s22, s15, 0x12800
	s_add_u32 s26, s20, 0x1000000
	s_addc_u32 s27, s21, 0
	s_add_u32 s28, s20, 0x1400000
	s_addc_u32 s29, s21, 0
	s_add_u32 s30, s20, 0x2a00000
	s_addc_u32 s31, s21, 0
	s_cmpk_gt_i32 s96, 0xff
	v_and_b32_e32 v235, 60, v229
	v_or_b32_e32 v233, 16, v232
	v_writelane_b32 v255, s37, 10
	s_cbranch_scc1 .LBB0_144
	s_add_u32 s98, s20, 0x5600000
	s_addc_u32 s99, s21, 0
	v_lshlrev_b32_e32 v1, 3, v229
	s_add_u32 s15, s20, 0x9600000
	v_and_b32_e32 v0, 31, v164
	v_lshrrev_b32_e32 v178, 5, v229
	v_and_b32_e32 v18, 24, v1
	s_addc_u32 s40, s21, 0
	v_lshl_add_u32 v19, v0, 2, s22
	v_mul_u32_u24_e32 v20, 0x84, v178
	v_mul_u32_u24_e32 v1, 0x84, v18
	s_lshl_b32 s16, s96, 6
	v_writelane_b32 v255, s22, 11
	v_add3_u32 v1, s22, v1, v235
	v_cmp_gt_u32_e64 s[42:43], 8, v0
	v_mov_b32_e32 v179, v163
	s_add_i32 s41, s16, 0xfffffe40
	s_lshl_b32 s22, s80, 6
	v_mov_b32_e32 v176, v163
	v_mov_b32_e32 v177, v163
	s_waitcnt vmcnt(0)
	v_mov_b32_e32 v2, v163
	v_mov_b32_e32 v3, v163
	v_mov_b32_e32 v4, v163
	v_mov_b32_e32 v5, v163
	v_mov_b32_e32 v6, v163
	v_mov_b32_e32 v7, v163
	v_mov_b32_e32 v8, v163
	v_mov_b32_e32 v9, v163
	v_mov_b32_e32 v10, v163
	v_mov_b32_e32 v11, v163
	v_mov_b32_e32 v12, v163
	v_mov_b32_e32 v13, v163
	v_mov_b32_e32 v14, v163
	v_mov_b32_e32 v15, v163
	v_mov_b32_e32 v16, v163
	v_mov_b32_e32 v17, v163
	v_mov_b32_e32 v234, 0x400
	v_mov_b32_e32 v236, 0
	s_mov_b64 s[36:37], 0
	v_mov_b64_e32 v[170:171], s[18:19]
	v_mov_b64_e32 v[172:173], s[54:55]
	v_lshlrev_b32_e32 v162, 2, v0
	v_lshlrev_b32_e32 v180, 1, v18
	v_add_u32_e32 v237, v19, v20
	v_mov_b32_e32 v0, 0
	v_mov_b32_e32 v174, 0
	s_branch .LBB0_35

.LBB0_260:
	s_waitcnt vmcnt(0)
	v_and_b32_e32 v90, 63, v137
	v_lshrrev_b32_e32 v89, 6, v137
	s_nop 0
	v_readfirstlane_b32 s100, v89
	v_and_b32_e32 v84, 31, v90
	v_lshrrev_b32_e32 v86, 5, v90
	v_and_b32_e32 v88, 7, v90
	v_lshrrev_b32_e32 v87, 3, v90
	v_lshlrev_b32_e32 v85, 5, v88
	s_mul_i32 s101, s100, 0x2100
	v_mul_u32_u24_e32 v89, 33, v86
	v_add_u32_e32 v89, v89, v84
	v_lshl_add_u32 v81, v89, 2, s101
	v_mul_u32_u24_e32 v89, 0x108, v88
	v_add_u32_e32 v89, v89, v87
	v_lshl_add_u32 v82, v89, 2, s101
	s_lshl_b32 s15, s12, 3
	s_add_i32 s15, s15, s100
	s_cmp_ge_u32 s15, 7808
	s_cbranch_scc1 .Lcv1_done
.Lcv1_loop:
	s_cmp_ge_u32 s15, 0x1880
	s_cselect_b32 s17, 1, 0
	s_mul_i32 s16, s17, 0x1880
	s_sub_i32 s16, s15, s16
	s_cmp_lt_u32 s16, 0x600
	s_cbranch_scc1 .Lcv1_in
	s_cmp_lt_u32 s16, 0x800
	s_cbranch_scc1 .Lcv1_out
	s_cmp_lt_u32 s16, 0x1300
	s_cbranch_scc1 .Lcv1_gu
	s_sub_i32 s16, s16, 0x1300
	s_lshr_b32 s20, s16, 5
	s_and_b32 s21, s16, 31
	s_lshl_b32 s21, s21, 5
	s_mov_b32 s22, s21
	s_mov_b32 s23, 32
	s_load_dwordx2 s[24:25], s[84:85], 0x90
	s_mov_b64 s[26:27], 0
	s_movk_i32 s30, 0x400
	s_movk_i32 s31, 0xb00
	s_mul_i32 vcc_lo, s17, 0xb00000
	s_mul_i32 vcc_hi, s17, 0x580000
	s_add_i32 vcc_hi, vcc_hi, 0x2a00000
	s_branch .Lcv1_dec
.Lcv1_in:
	s_mul_i32 s20, s16, 0x2ab
	s_lshr_b32 s20, s20, 16
	s_mul_i32 s21, s20, 0x60
	s_sub_i32 s21, s16, s21
	s_lshl_b32 s21, s21, 5
	s_mov_b32 s22, s21
	s_mov_b32 s23, 32
	s_cmp_lt_u32 s21, 0x900
	s_cbranch_scc1 .Lcv1_in2
	s_add_i32 s22, s21, 8
	s_cmp_lt_u32 s21, 0xb00
	s_cbranch_scc1 .Lcv1_in2
	s_movk_i32 s22, 0x900
	s_mov_b32 s23, 8
	s_cmp_eq_u32 s21, 0xb00
	s_cbranch_scc1 .Lcv1_in2
	s_mov_b32 s22, 0
	s_mov_b32 s23, 0
.Lcv1_in2:
	s_load_dwordx2 s[24:25], s[84:85], 0x10
	s_load_dwordx2 s[26:27], s[84:85], 0x8
	s_movk_i32 s30, 0xb08
	s_movk_i32 s31, 0x400
	s_mul_i32 vcc_lo, s17, 0xb08000
	s_mul_i32 vcc_hi, s17, 0x600000
	s_add_i32 vcc_hi, vcc_hi, 0x400000
	s_branch .Lcv1_dec
.Lcv1_out:
	s_sub_i32 s16, s16, 0x600
	s_lshr_b32 s20, s16, 5
	s_and_b32 s21, s16, 31
	s_lshl_b32 s21, s21, 5
	s_mov_b32 s22, s21
	s_mov_b32 s23, 32
	s_load_dwordx2 s[24:25], s[84:85], 0x70
	s_mov_b64 s[26:27], 0
	s_movk_i32 s30, 0x400
	s_movk_i32 s31, 0x400
	s_mul_i32 vcc_lo, s17, 0x400000
	s_mul_i32 vcc_hi, s17, 0x200000
	s_add_i32 vcc_hi, vcc_hi, 0x1000000
	s_branch .Lcv1_dec
.Lcv1_gu:
	s_sub_i32 s16, s16, 0x800
	s_mul_i32 s20, s16, 0xba3
	s_lshr_b32 s20, s20, 19
	s_mul_i32 s21, s20, 0xb0
	s_sub_i32 s21, s16, s21
	s_lshl_b32 s21, s21, 5
	s_lshr_b32 s22, s21, 8
	s_lshl_b32 s22, s22, 7
	s_and_b32 s100, s21, 0x7f
	s_add_i32 s22, s22, s100
	s_mov_b32 s23, 32
	s_bitcmp1_b32 s21, 7
	s_cbranch_scc1 .Lcv1_gu_up
	s_load_dwordx2 s[24:25], s[84:85], 0x80
	s_branch .Lcv1_gu2
.Lcv1_gu_up:
	s_load_dwordx2 s[24:25], s[84:85], 0x88
.Lcv1_gu2:
	s_load_dwordx2 s[26:27], s[84:85], 0x78
	s_movk_i32 s30, 0xb00
	s_movk_i32 s31, 0x400
	s_mul_i32 vcc_lo, s17, 0xb00000
	s_mul_i32 vcc_hi, s17, 0xb00000
	s_add_i32 vcc_hi, vcc_hi, 0x1400000
.Lcv1_dec:
	s_load_dwordx2 s[28:29], s[84:85], 0xa8
	s_lshl_b32 s100, s20, 6
	s_mul_i32 s101, s100, s30
	s_add_i32 s101, s101, s22
	s_lshl_b32 s101, s101, 2
	s_add_u32 vcc_lo, vcc_lo, s101
	s_mul_i32 s101, s21, s31
	s_add_i32 s101, s101, s100
	s_lshl_b32 s101, s101, 1
	s_add_u32 vcc_hi, vcc_hi, s101
	s_lshl_b32 s100, s100, 2
	s_lshl_b32 s101, s17, 12
	s_add_u32 s100, s100, s101
	s_waitcnt lgkmcnt(0)
	s_add_u32 s24, s24, vcc_lo
	s_addc_u32 s25, s25, 0
	s_add_u32 s28, s28, vcc_hi
	s_addc_u32 s29, s29, 0
	v_mul_u32_u24_e32 v89, s30, v86
	v_add_lshl_u32 v80, v89, v84, 2
	v_mul_u32_u24_e32 v89, s31, v87
	v_lshlrev_b32_e32 v89, 1, v89
	v_lshl_add_u32 v83, v88, 4, v89
	s_cmp_lg_u64 s[26:27], 0
	s_cbranch_scc0 .Lcv1_nog
	s_add_u32 s26, s26, s100
	s_addc_u32 s27, s27, 0
	global_load_dwordx4 v[32:35], v85, s[26:27]
	global_load_dwordx4 v[36:39], v85, s[26:27] offset:16
	s_branch .Lcv1_ld
.Lcv1_nog:
	v_mov_b32_e32 v32, 1.0
	v_mov_b32_e32 v33, 1.0
	v_mov_b32_e32 v34, 1.0
	v_mov_b32_e32 v35, 1.0
	v_mov_b32_e32 v36, 1.0
	v_mov_b32_e32 v37, 1.0
	v_mov_b32_e32 v38, 1.0
	v_mov_b32_e32 v39, 1.0
.Lcv1_ld:
	s_lshl_b32 s100, s30, 3
	global_load_dword v0, v80, s[24:25] nt
	s_add_u32 s24, s24, s100
	s_addc_u32 s25, s25, 0
	global_load_dword v1, v80, s[24:25] nt
	s_add_u32 s24, s24, s100
	s_addc_u32 s25, s25, 0
	global_load_dword v2, v80, s[24:25] nt
	s_add_u32 s24, s24, s100
	s_addc_u32 s25, s25, 0
	global_load_dword v3, v80, s[24:25] nt
	s_add_u32 s24, s24, s100
	s_addc_u32 s25, s25, 0
	global_load_dword v4, v80, s[24:25] nt
	s_add_u32 s24, s24, s100
	s_addc_u32 s25, s25, 0
	global_load_dword v5, v80, s[24:25] nt
	s_add_u32 s24, s24, s100
	s_addc_u32 s25, s25, 0
	global_load_dword v6, v80, s[24:25] nt
	s_add_u32 s24, s24, s100
	s_addc_u32 s25, s25, 0
	global_load_dword v7, v80, s[24:25] nt
	s_add_u32 s24, s24, s100
	s_addc_u32 s25, s25, 0
	global_load_dword v8, v80, s[24:25] nt
	s_add_u32 s24, s24, s100
	s_addc_u32 s25, s25, 0
	global_load_dword v9, v80, s[24:25] nt
	s_add_u32 s24, s24, s100
	s_addc_u32 s25, s25, 0
	global_load_dword v10, v80, s[24:25] nt
	s_add_u32 s24, s24, s100
	s_addc_u32 s25, s25, 0
	global_load_dword v11, v80, s[24:25] nt
	s_add_u32 s24, s24, s100
	s_addc_u32 s25, s25, 0
	global_load_dword v12, v80, s[24:25] nt
	s_add_u32 s24, s24, s100
	s_addc_u32 s25, s25, 0
	global_load_dword v13, v80, s[24:25] nt
	s_add_u32 s24, s24, s100
	s_addc_u32 s25, s25, 0
	global_load_dword v14, v80, s[24:25] nt
	s_add_u32 s24, s24, s100
	s_addc_u32 s25, s25, 0
	global_load_dword v15, v80, s[24:25] nt
	s_add_u32 s24, s24, s100
	s_addc_u32 s25, s25, 0
	global_load_dword v16, v80, s[24:25] nt
	s_add_u32 s24, s24, s100
	s_addc_u32 s25, s25, 0
	global_load_dword v17, v80, s[24:25] nt
	s_add_u32 s24, s24, s100
	s_addc_u32 s25, s25, 0
	global_load_dword v18, v80, s[24:25] nt
	s_add_u32 s24, s24, s100
	s_addc_u32 s25, s25, 0
	global_load_dword v19, v80, s[24:25] nt
	s_add_u32 s24, s24, s100
	s_addc_u32 s25, s25, 0
	global_load_dword v20, v80, s[24:25] nt
	s_add_u32 s24, s24, s100
	s_addc_u32 s25, s25, 0
	global_load_dword v21, v80, s[24:25] nt
	s_add_u32 s24, s24, s100
	s_addc_u32 s25, s25, 0
	global_load_dword v22, v80, s[24:25] nt
	s_add_u32 s24, s24, s100
	s_addc_u32 s25, s25, 0
	global_load_dword v23, v80, s[24:25] nt
	s_add_u32 s24, s24, s100
	s_addc_u32 s25, s25, 0
	global_load_dword v24, v80, s[24:25] nt
	s_add_u32 s24, s24, s100
	s_addc_u32 s25, s25, 0
	global_load_dword v25, v80, s[24:25] nt
	s_add_u32 s24, s24, s100
	s_addc_u32 s25, s25, 0
	global_load_dword v26, v80, s[24:25] nt
	s_add_u32 s24, s24, s100
	s_addc_u32 s25, s25, 0
	global_load_dword v27, v80, s[24:25] nt
	s_add_u32 s24, s24, s100
	s_addc_u32 s25, s25, 0
	global_load_dword v28, v80, s[24:25] nt
	s_add_u32 s24, s24, s100
	s_addc_u32 s25, s25, 0
	global_load_dword v29, v80, s[24:25] nt
	s_add_u32 s24, s24, s100
	s_addc_u32 s25, s25, 0
	global_load_dword v30, v80, s[24:25] nt
	s_add_u32 s24, s24, s100
	s_addc_u32 s25, s25, 0
	global_load_dword v31, v80, s[24:25] nt
	s_lshl_b32 s101, s31, 4
	s_waitcnt vmcnt(0)
	s_cmp_eq_u32 s23, 32
	s_cbranch_scc1 .Lcv1_nomask
	v_cmp_gt_u32_e32 vcc, s23, v84
	s_nop 1
	v_cndmask_b32_e32 v0, 0, v0, vcc
	v_cndmask_b32_e32 v1, 0, v1, vcc
	v_cndmask_b32_e32 v2, 0, v2, vcc
	v_cndmask_b32_e32 v3, 0, v3, vcc
	v_cndmask_b32_e32 v4, 0, v4, vcc
	v_cndmask_b32_e32 v5, 0, v5, vcc
	v_cndmask_b32_e32 v6, 0, v6, vcc
	v_cndmask_b32_e32 v7, 0, v7, vcc
	v_cndmask_b32_e32 v8, 0, v8, vcc
	v_cndmask_b32_e32 v9, 0, v9, vcc
	v_cndmask_b32_e32 v10, 0, v10, vcc
	v_cndmask_b32_e32 v11, 0, v11, vcc
	v_cndmask_b32_e32 v12, 0, v12, vcc
	v_cndmask_b32_e32 v13, 0, v13, vcc
	v_cndmask_b32_e32 v14, 0, v14, vcc
	v_cndmask_b32_e32 v15, 0, v15, vcc
	v_cndmask_b32_e32 v16, 0, v16, vcc
	v_cndmask_b32_e32 v17, 0, v17, vcc
	v_cndmask_b32_e32 v18, 0, v18, vcc
	v_cndmask_b32_e32 v19, 0, v19, vcc
	v_cndmask_b32_e32 v20, 0, v20, vcc
	v_cndmask_b32_e32 v21, 0, v21, vcc
	v_cndmask_b32_e32 v22, 0, v22, vcc
	v_cndmask_b32_e32 v23, 0, v23, vcc
	v_cndmask_b32_e32 v24, 0, v24, vcc
	v_cndmask_b32_e32 v25, 0, v25, vcc
	v_cndmask_b32_e32 v26, 0, v26, vcc
	v_cndmask_b32_e32 v27, 0, v27, vcc
	v_cndmask_b32_e32 v28, 0, v28, vcc
	v_cndmask_b32_e32 v29, 0, v29, vcc
	v_cndmask_b32_e32 v30, 0, v30, vcc
	v_cndmask_b32_e32 v31, 0, v31, vcc
.Lcv1_nomask:
	ds_write_b32 v81, v0
	ds_write_b32 v81, v1 offset:264
	ds_write_b32 v81, v2 offset:528
	ds_write_b32 v81, v3 offset:792
	ds_write_b32 v81, v4 offset:1056
	ds_write_b32 v81, v5 offset:1320
	ds_write_b32 v81, v6 offset:1584
	ds_write_b32 v81, v7 offset:1848
	ds_write_b32 v81, v8 offset:2112
	ds_write_b32 v81, v9 offset:2376
	ds_write_b32 v81, v10 offset:2640
	ds_write_b32 v81, v11 offset:2904
	ds_write_b32 v81, v12 offset:3168
	ds_write_b32 v81, v13 offset:3432
	ds_write_b32 v81, v14 offset:3696
	ds_write_b32 v81, v15 offset:3960
	ds_write_b32 v81, v16 offset:4224
	ds_write_b32 v81, v17 offset:4488
	ds_write_b32 v81, v18 offset:4752
	ds_write_b32 v81, v19 offset:5016
	ds_write_b32 v81, v20 offset:5280
	ds_write_b32 v81, v21 offset:5544
	ds_write_b32 v81, v22 offset:5808
	ds_write_b32 v81, v23 offset:6072
	ds_write_b32 v81, v24 offset:6336
	ds_write_b32 v81, v25 offset:6600
	ds_write_b32 v81, v26 offset:6864
	ds_write_b32 v81, v27 offset:7128
	ds_write_b32 v81, v28 offset:7392
	ds_write_b32 v81, v29 offset:7656
	ds_write_b32 v81, v30 offset:7920
	ds_write_b32 v81, v31 offset:8184
	ds_read2_b32 v[40:41], v82 offset1:33
	ds_read2_b32 v[42:43], v82 offset0:66 offset1:99
	ds_read2_b32 v[44:45], v82 offset0:132 offset1:165
	ds_read2_b32 v[46:47], v82 offset0:198 offset1:231
	ds_read2_b32 v[48:49], v82 offset0:8 offset1:41
	ds_read2_b32 v[50:51], v82 offset0:74 offset1:107
	ds_read2_b32 v[52:53], v82 offset0:140 offset1:173
	ds_read2_b32 v[54:55], v82 offset0:206 offset1:239
	ds_read2_b32 v[56:57], v82 offset0:16 offset1:49
	ds_read2_b32 v[58:59], v82 offset0:82 offset1:115
	ds_read2_b32 v[60:61], v82 offset0:148 offset1:181
	ds_read2_b32 v[62:63], v82 offset0:214 offset1:247
	ds_read2_b32 v[64:65], v82 offset0:24 offset1:57
	ds_read2_b32 v[66:67], v82 offset0:90 offset1:123
	ds_read2_b32 v[68:69], v82 offset0:156 offset1:189
	ds_read2_b32 v[70:71], v82 offset0:222 offset1:255
	s_waitcnt lgkmcnt(0)
	v_mul_f32_e32 v40, v32, v40
	v_mul_f32_e32 v41, v33, v41
	v_mul_f32_e32 v42, v34, v42
	v_mul_f32_e32 v43, v35, v43
	v_mul_f32_e32 v44, v36, v44
	v_mul_f32_e32 v45, v37, v45
	v_mul_f32_e32 v46, v38, v46
	v_mul_f32_e32 v47, v39, v47
	v_cvt_pk_bf16_f32 v72, v40, v41
	v_cvt_pk_bf16_f32 v73, v42, v43
	v_cvt_pk_bf16_f32 v74, v44, v45
	v_cvt_pk_bf16_f32 v75, v46, v47
	global_store_dwordx4 v83, v[72:75], s[28:29]
	v_add_u32_e32 v83, s101, v83
	v_mul_f32_e32 v48, v32, v48
	v_mul_f32_e32 v49, v33, v49
	v_mul_f32_e32 v50, v34, v50
	v_mul_f32_e32 v51, v35, v51
	v_mul_f32_e32 v52, v36, v52
	v_mul_f32_e32 v53, v37, v53
	v_mul_f32_e32 v54, v38, v54
	v_mul_f32_e32 v55, v39, v55
	v_cvt_pk_bf16_f32 v76, v48, v49
	v_cvt_pk_bf16_f32 v77, v50, v51
	v_cvt_pk_bf16_f32 v78, v52, v53
	v_cvt_pk_bf16_f32 v79, v54, v55
	global_store_dwordx4 v83, v[76:79], s[28:29]
	v_add_u32_e32 v83, s101, v83
	v_mul_f32_e32 v56, v32, v56
	v_mul_f32_e32 v57, v33, v57
	v_mul_f32_e32 v58, v34, v58
	v_mul_f32_e32 v59, v35, v59
	v_mul_f32_e32 v60, v36, v60
	v_mul_f32_e32 v61, v37, v61
	v_mul_f32_e32 v62, v38, v62
	v_mul_f32_e32 v63, v39, v63
	v_cvt_pk_bf16_f32 v72, v56, v57
	v_cvt_pk_bf16_f32 v73, v58, v59
	v_cvt_pk_bf16_f32 v74, v60, v61
	v_cvt_pk_bf16_f32 v75, v62, v63
	global_store_dwordx4 v83, v[72:75], s[28:29]
	v_add_u32_e32 v83, s101, v83
	v_mul_f32_e32 v64, v32, v64
	v_mul_f32_e32 v65, v33, v65
	v_mul_f32_e32 v66, v34, v66
	v_mul_f32_e32 v67, v35, v67
	v_mul_f32_e32 v68, v36, v68
	v_mul_f32_e32 v69, v37, v69
	v_mul_f32_e32 v70, v38, v70
	v_mul_f32_e32 v71, v39, v71
	v_cvt_pk_bf16_f32 v76, v64, v65
	v_cvt_pk_bf16_f32 v77, v66, v67
	v_cvt_pk_bf16_f32 v78, v68, v69
	v_cvt_pk_bf16_f32 v79, v70, v71
	global_store_dwordx4 v83, v[76:79], s[28:29]
	s_add_i32 s15, s15, 2048
	s_cmp_lt_u32 s15, 7808
	s_cbranch_scc1 .Lcv1_loop
.Lcv1_done:
.LBB0_334:
	s_mov_b64 s[20:21], 0

.LBB0_565:
	s_waitcnt vmcnt(0)
	v_readlane_b32 s0, v254, 55
	v_readlane_b32 s46, v254, 57
	v_readlane_b32 s52, v254, 59
	v_readlane_b32 s54, v254, 62
	v_readlane_b32 s56, v255, 0
	v_readlane_b32 s58, v255, 2
	s_barrier
	v_readlane_b32 s2, v254, 54
	v_readlane_b32 s1, v254, 56
	v_readlane_b32 s47, v254, 58
	v_readlane_b32 s53, v254, 60
	v_readlane_b32 s45, v254, 61
	v_readlane_b32 s55, v254, 63
	v_readlane_b32 s57, v255, 1
	v_readlane_b32 s59, v255, 3
	s_cmp_lg_u32 s68, 6
	s_cbranch_scc1 .Lcv2_done
	s_cmp_lt_u32 s2, 128
	s_cbranch_scc1 .Lcv2_done
	s_waitcnt vmcnt(0)
	v_and_b32_e32 v90, 63, v137
	v_lshrrev_b32_e32 v89, 6, v137
	s_nop 0
	v_readfirstlane_b32 s100, v89
	v_and_b32_e32 v84, 31, v90
	v_lshrrev_b32_e32 v86, 5, v90
	v_and_b32_e32 v88, 7, v90
	v_lshrrev_b32_e32 v87, 3, v90
	v_lshlrev_b32_e32 v85, 5, v88
	s_mul_i32 s101, s100, 0x2100
	v_mul_u32_u24_e32 v89, 33, v86
	v_add_u32_e32 v89, v89, v84
	v_lshl_add_u32 v81, v89, 2, s101
	v_mul_u32_u24_e32 v89, 0x108, v88
	v_add_u32_e32 v89, v89, v87
	v_lshl_add_u32 v82, v89, 2, s101
	s_sub_i32 s15, s2, 128
	s_lshl_b32 s15, s15, 3
	s_add_i32 s15, s15, s100
	s_add_i32 s15, s15, 7808
	s_cmp_ge_u32 s15, 12544
	s_cbranch_scc1 .Lcv2_done
.Lcv2_loop:
	s_cmp_ge_u32 s15, 0x1880
	s_cselect_b32 s17, 1, 0
	s_mul_i32 s16, s17, 0x1880
	s_sub_i32 s16, s15, s16
	s_cmp_lt_u32 s16, 0x600
	s_cbranch_scc1 .Lcv2_in
	s_cmp_lt_u32 s16, 0x800
	s_cbranch_scc1 .Lcv2_out
	s_cmp_lt_u32 s16, 0x1300
	s_cbranch_scc1 .Lcv2_gu
	s_sub_i32 s16, s16, 0x1300
	s_lshr_b32 s20, s16, 5
	s_and_b32 s21, s16, 31
	s_lshl_b32 s21, s21, 5
	s_mov_b32 s22, s21
	s_mov_b32 s23, 32
	s_load_dwordx2 s[24:25], s[0:1], 0x90
	s_mov_b64 s[26:27], 0
	s_movk_i32 s30, 0x400
	s_movk_i32 s31, 0xb00
	s_mul_i32 vcc_lo, s17, 0xb00000
	s_mul_i32 vcc_hi, s17, 0x580000
	s_add_i32 vcc_hi, vcc_hi, 0x2a00000
	s_branch .Lcv2_dec

.Lcv2_in2:
	s_load_dwordx2 s[24:25], s[0:1], 0x10
	s_load_dwordx2 s[26:27], s[0:1], 0x8
	s_movk_i32 s30, 0xb08
	s_movk_i32 s31, 0x400
	s_mul_i32 vcc_lo, s17, 0xb08000
	s_mul_i32 vcc_hi, s17, 0x600000
	s_add_i32 vcc_hi, vcc_hi, 0x400000
	s_branch .Lcv2_dec
.Lcv2_out:
	s_sub_i32 s16, s16, 0x600
	s_lshr_b32 s20, s16, 5
	s_and_b32 s21, s16, 31
	s_lshl_b32 s21, s21, 5
	s_mov_b32 s22, s21
	s_mov_b32 s23, 32
	s_load_dwordx2 s[24:25], s[0:1], 0x70
	s_mov_b64 s[26:27], 0
	s_movk_i32 s30, 0x400
	s_movk_i32 s31, 0x400
	s_mul_i32 vcc_lo, s17, 0x400000
	s_mul_i32 vcc_hi, s17, 0x200000
	s_add_i32 vcc_hi, vcc_hi, 0x1000000
	s_branch .Lcv2_dec
.Lcv2_gu:
	s_sub_i32 s16, s16, 0x800
	s_mul_i32 s20, s16, 0xba3
	s_lshr_b32 s20, s20, 19
	s_mul_i32 s21, s20, 0xb0
	s_sub_i32 s21, s16, s21
	s_lshl_b32 s21, s21, 5
	s_lshr_b32 s22, s21, 8
	s_lshl_b32 s22, s22, 7
	s_and_b32 s100, s21, 0x7f
	s_add_i32 s22, s22, s100
	s_mov_b32 s23, 32
	s_bitcmp1_b32 s21, 7
	s_cbranch_scc1 .Lcv2_gu_up
	s_load_dwordx2 s[24:25], s[0:1], 0x80
	s_branch .Lcv2_gu2
.Lcv2_gu_up:
	s_load_dwordx2 s[24:25], s[0:1], 0x88
.Lcv2_gu2:
	s_load_dwordx2 s[26:27], s[0:1], 0x78
	s_movk_i32 s30, 0xb00
	s_movk_i32 s31, 0x400
	s_mul_i32 vcc_lo, s17, 0xb00000
	s_mul_i32 vcc_hi, s17, 0xb00000
	s_add_i32 vcc_hi, vcc_hi, 0x1400000
.Lcv2_dec:
	s_load_dwordx2 s[28:29], s[0:1], 0xa8
	s_lshl_b32 s100, s20, 6
	s_mul_i32 s101, s100, s30
	s_add_i32 s101, s101, s22
	s_lshl_b32 s101, s101, 2
	s_add_u32 vcc_lo, vcc_lo, s101
	s_mul_i32 s101, s21, s31
	s_add_i32 s101, s101, s100
	s_lshl_b32 s101, s101, 1
	s_add_u32 vcc_hi, vcc_hi, s101
	s_lshl_b32 s100, s100, 2
	s_lshl_b32 s101, s17, 12
	s_add_u32 s100, s100, s101
	s_waitcnt lgkmcnt(0)
	s_add_u32 s24, s24, vcc_lo
	s_addc_u32 s25, s25, 0
	s_add_u32 s28, s28, vcc_hi
	s_addc_u32 s29, s29, 0
	v_mul_u32_u24_e32 v89, s30, v86
	v_add_lshl_u32 v80, v89, v84, 2
	v_mul_u32_u24_e32 v89, s31, v87
	v_lshlrev_b32_e32 v89, 1, v89
	v_lshl_add_u32 v83, v88, 4, v89
	s_cmp_lg_u64 s[26:27], 0
	s_cbranch_scc0 .Lcv2_nog
	s_add_u32 s26, s26, s100
	s_addc_u32 s27, s27, 0
	global_load_dwordx4 v[32:35], v85, s[26:27]
	global_load_dwordx4 v[36:39], v85, s[26:27] offset:16
	s_branch .Lcv2_ld

.Lcv2_nomask:
	ds_write_b32 v81, v0
	ds_write_b32 v81, v1 offset:264
	ds_write_b32 v81, v2 offset:528
	ds_write_b32 v81, v3 offset:792
	ds_write_b32 v81, v4 offset:1056
	ds_write_b32 v81, v5 offset:1320
	ds_write_b32 v81, v6 offset:1584
	ds_write_b32 v81, v7 offset:1848
	ds_write_b32 v81, v8 offset:2112
	ds_write_b32 v81, v9 offset:2376
	ds_write_b32 v81, v10 offset:2640
	ds_write_b32 v81, v11 offset:2904
	ds_write_b32 v81, v12 offset:3168
	ds_write_b32 v81, v13 offset:3432
	ds_write_b32 v81, v14 offset:3696
	ds_write_b32 v81, v15 offset:3960
	ds_write_b32 v81, v16 offset:4224
	ds_write_b32 v81, v17 offset:4488
	ds_write_b32 v81, v18 offset:4752
	ds_write_b32 v81, v19 offset:5016
	ds_write_b32 v81, v20 offset:5280
	ds_write_b32 v81, v21 offset:5544
	ds_write_b32 v81, v22 offset:5808
	ds_write_b32 v81, v23 offset:6072
	ds_write_b32 v81, v24 offset:6336
	ds_write_b32 v81, v25 offset:6600
	ds_write_b32 v81, v26 offset:6864
	ds_write_b32 v81, v27 offset:7128
	ds_write_b32 v81, v28 offset:7392
	ds_write_b32 v81, v29 offset:7656
	ds_write_b32 v81, v30 offset:7920
	ds_write_b32 v81, v31 offset:8184
	ds_read2_b32 v[40:41], v82 offset1:33
	ds_read2_b32 v[42:43], v82 offset0:66 offset1:99
	ds_read2_b32 v[44:45], v82 offset0:132 offset1:165
	ds_read2_b32 v[46:47], v82 offset0:198 offset1:231
	ds_read2_b32 v[48:49], v82 offset0:8 offset1:41
	ds_read2_b32 v[50:51], v82 offset0:74 offset1:107
	ds_read2_b32 v[52:53], v82 offset0:140 offset1:173
	ds_read2_b32 v[54:55], v82 offset0:206 offset1:239
	ds_read2_b32 v[56:57], v82 offset0:16 offset1:49
	ds_read2_b32 v[58:59], v82 offset0:82 offset1:115
	ds_read2_b32 v[60:61], v82 offset0:148 offset1:181
	ds_read2_b32 v[62:63], v82 offset0:214 offset1:247
	ds_read2_b32 v[64:65], v82 offset0:24 offset1:57
	ds_read2_b32 v[66:67], v82 offset0:90 offset1:123
	ds_read2_b32 v[68:69], v82 offset0:156 offset1:189
	ds_read2_b32 v[70:71], v82 offset0:222 offset1:255
	s_waitcnt lgkmcnt(0)
	v_mul_f32_e32 v40, v32, v40
	v_mul_f32_e32 v41, v33, v41
	v_mul_f32_e32 v42, v34, v42
	v_mul_f32_e32 v43, v35, v43
	v_mul_f32_e32 v44, v36, v44
	v_mul_f32_e32 v45, v37, v45
	v_mul_f32_e32 v46, v38, v46
	v_mul_f32_e32 v47, v39, v47
	v_cvt_pk_bf16_f32 v72, v40, v41
	v_cvt_pk_bf16_f32 v73, v42, v43
	v_cvt_pk_bf16_f32 v74, v44, v45
	v_cvt_pk_bf16_f32 v75, v46, v47
	global_store_dwordx4 v83, v[72:75], s[28:29]
	v_add_u32_e32 v83, s101, v83
	v_mul_f32_e32 v48, v32, v48
	v_mul_f32_e32 v49, v33, v49
	v_mul_f32_e32 v50, v34, v50
	v_mul_f32_e32 v51, v35, v51
	v_mul_f32_e32 v52, v36, v52
	v_mul_f32_e32 v53, v37, v53
	v_mul_f32_e32 v54, v38, v54
	v_mul_f32_e32 v55, v39, v55
	v_cvt_pk_bf16_f32 v76, v48, v49
	v_cvt_pk_bf16_f32 v77, v50, v51
	v_cvt_pk_bf16_f32 v78, v52, v53
	v_cvt_pk_bf16_f32 v79, v54, v55
	global_store_dwordx4 v83, v[76:79], s[28:29]
	v_add_u32_e32 v83, s101, v83
	v_mul_f32_e32 v56, v32, v56
	v_mul_f32_e32 v57, v33, v57
	v_mul_f32_e32 v58, v34, v58
	v_mul_f32_e32 v59, v35, v59
	v_mul_f32_e32 v60, v36, v60
	v_mul_f32_e32 v61, v37, v61
	v_mul_f32_e32 v62, v38, v62
	v_mul_f32_e32 v63, v39, v63
	v_cvt_pk_bf16_f32 v72, v56, v57
	v_cvt_pk_bf16_f32 v73, v58, v59
	v_cvt_pk_bf16_f32 v74, v60, v61
	v_cvt_pk_bf16_f32 v75, v62, v63
	global_store_dwordx4 v83, v[72:75], s[28:29]
	v_add_u32_e32 v83, s101, v83
	v_mul_f32_e32 v64, v32, v64
	v_mul_f32_e32 v65, v33, v65
	v_mul_f32_e32 v66, v34, v66
	v_mul_f32_e32 v67, v35, v67
	v_mul_f32_e32 v68, v36, v68
	v_mul_f32_e32 v69, v37, v69
	v_mul_f32_e32 v70, v38, v70
	v_mul_f32_e32 v71, v39, v71
	v_cvt_pk_bf16_f32 v76, v64, v65
	v_cvt_pk_bf16_f32 v77, v66, v67
	v_cvt_pk_bf16_f32 v78, v68, v69
	v_cvt_pk_bf16_f32 v79, v70, v71
	global_store_dwordx4 v83, v[76:79], s[28:29]
	s_add_i32 s15, s15, 1024
	s_cmp_lt_u32 s15, 12544
	s_cbranch_scc1 .Lcv2_loop
.Lcv2_done:
.LBB0_566:
	v_readlane_b32 s22, v255, 4
	v_readlane_b32 s23, v255, 5
